# code placement: every 8-byte instruction of the hand-written S2 / S3 regions starts on an 8-byte boundary
# baseline (speedup 1.0000x reference)
.LBB0_374:
	v_bfe_u32 v127, v132, 6, 2
	s_movk_i32 s4, 0x100
	v_lshlrev_b32_e32 v116, 4, v127
	v_mov_b32_e32 v96, s38
	v_cmp_gt_u32_e32 vcc, s4, v132
	v_or_b32_e32 v97, v116, v142
	v_and_b32_e32 v120, 48, v132
	v_cndmask_b32_e32 v96, 0, v96, vcc
	v_mul_u32_u24_e32 v97, 0x110, v97
	v_add_u32_e32 v128, 0, v120
	s_waitcnt lgkmcnt(0)
	s_barrier
	v_lshrrev_b32_e32 v121, 4, v143
	v_lshlrev_b32_e32 v122, 2, v142
	v_lshlrev_b32_e32 v130, 1, v142
	v_lshlrev_b32_e32 v119, 2, v121
	v_lshrrev_b32_e64 v116, 6, v198
	v_and_b32_e32 v128, 15, v198
	v_readfirstlane_b32 s4, v116
	v_bfe_u32 v133, v198, 4, 2
	s_and_b32 s5, s4, 3
	s_lshr_b32 s6, s4, 2
	s_movk_i32 s7, 272
	v_lshlrev_b32_e32 v134, 4, v133
	v_mad_u32_u24 v117, v128, s7, v134
	s_mul_i32 s7, s5, 4352
	s_cmp_eq_u32 s6, 0
	s_nop 0
	s_cselect_b32 s10, 17408, 0
	s_add_u32 s7, s7, s10
	v_add_u32_e32 v116, s7, v117
	v_add_u32_e32 v117, 17408, v117
	ds_read_b128 v[96:99], v116 offset:0
	ds_read_b128 v[100:103], v116 offset:64
	ds_read_b128 v[104:107], v116 offset:128
	ds_read_b128 v[108:111], v116 offset:192
	s_lshl_b32 s7, s5, 6
	s_nop 0
	v_lshl_add_u32 v134, v133, 4, s7
	v_add_u32_e32 v134, 0x1f700, v134
	ds_read_b128 v[146:149], v134
	ds_read_b128 v[124:127], v134 offset:256
	v_lshlrev_b32_e64 v134, 2, v128
	v_add_u32_e32 v134, 0x1f700, v134
	ds_read_b32 v237, v134 offset:0
	ds_read_b32 v238, v134 offset:64
	ds_read_b32 v239, v134 offset:128
	ds_read_b32 v123, v134 offset:192
	s_lshl_b32 s7, s5, 4
	s_nop 0
	v_lshl_add_u32 v116, v133, 2, s7
	ds_read_b128 v[112:115], v117 offset:0
	ds_read_b128 v[136:139], v117 offset:64
	s_waitcnt lgkmcnt(1)
	s_nop 0
	v_mfma_f32_16x16x32_bf16 v[240:243], v[96:99], v[112:115], 0
	ds_read_b128 v[112:115], v117 offset:128
	s_waitcnt lgkmcnt(1)
	s_nop 0
	v_mfma_f32_16x16x32_bf16 v[240:243], v[100:103], v[136:139], v[240:243]
	ds_read_b128 v[136:139], v117 offset:192
	s_waitcnt lgkmcnt(1)
	s_nop 0
	v_mfma_f32_16x16x32_bf16 v[240:243], v[104:107], v[112:115], v[240:243]
	s_waitcnt lgkmcnt(0)
	s_nop 0
	v_mfma_f32_16x16x32_bf16 v[240:243], v[108:111], v[136:139], v[240:243]
	s_cmp_lt_u32 s5, 1
	s_cbranch_scc1 .Ls2_skip1
	ds_read_b128 v[112:115], v117 offset:4352
	ds_read_b128 v[136:139], v117 offset:4416
	s_waitcnt lgkmcnt(1)
	s_nop 0
	v_mfma_f32_16x16x32_bf16 v[244:247], v[96:99], v[112:115], 0
	ds_read_b128 v[112:115], v117 offset:4480
	s_waitcnt lgkmcnt(1)
	s_nop 0
	v_mfma_f32_16x16x32_bf16 v[244:247], v[100:103], v[136:139], v[244:247]
	ds_read_b128 v[136:139], v117 offset:4544
	s_waitcnt lgkmcnt(1)
	s_nop 0
	v_mfma_f32_16x16x32_bf16 v[244:247], v[104:107], v[112:115], v[244:247]
	s_waitcnt lgkmcnt(0)
	s_nop 0
	v_mfma_f32_16x16x32_bf16 v[244:247], v[108:111], v[136:139], v[244:247]
	s_branch .Ls2_done1
.Ls2_skip1:
	v_mov_b32_e32 v244, 0
	v_mov_b32_e32 v245, 0
	v_mov_b32_e32 v246, 0
	v_mov_b32_e64 v247, 0
.Ls2_done1:
	s_cmp_lt_u32 s5, 2
	s_cbranch_scc1 .Ls2_skip2
	ds_read_b128 v[112:115], v117 offset:8704
	ds_read_b128 v[136:139], v117 offset:8768
	s_waitcnt lgkmcnt(1)
	s_nop 0
	v_mfma_f32_16x16x32_bf16 v[248:251], v[96:99], v[112:115], 0
	ds_read_b128 v[112:115], v117 offset:8832
	s_waitcnt lgkmcnt(1)
	s_nop 0
	v_mfma_f32_16x16x32_bf16 v[248:251], v[100:103], v[136:139], v[248:251]
	ds_read_b128 v[136:139], v117 offset:8896
	s_waitcnt lgkmcnt(1)
	s_nop 0
	v_mfma_f32_16x16x32_bf16 v[248:251], v[104:107], v[112:115], v[248:251]
	s_waitcnt lgkmcnt(0)
	s_nop 0
	v_mfma_f32_16x16x32_bf16 v[248:251], v[108:111], v[136:139], v[248:251]
	s_branch .Ls2_done2
.Ls2_skip2:
	v_mov_b32_e32 v248, 0
	v_mov_b32_e32 v249, 0
	v_mov_b32_e32 v250, 0
	v_mov_b32_e64 v251, 0
.Ls2_done2:
	s_cmp_lt_u32 s5, 3
	s_cbranch_scc1 .Ls2_skip3
	ds_read_b128 v[112:115], v117 offset:13056
	ds_read_b128 v[136:139], v117 offset:13120
	s_waitcnt lgkmcnt(1)
	s_nop 0
	v_mfma_f32_16x16x32_bf16 v[252:255], v[96:99], v[112:115], 0
	ds_read_b128 v[112:115], v117 offset:13184
	s_waitcnt lgkmcnt(1)
	s_nop 0
	v_mfma_f32_16x16x32_bf16 v[252:255], v[100:103], v[136:139], v[252:255]
	ds_read_b128 v[136:139], v117 offset:13248
	s_waitcnt lgkmcnt(1)
	s_nop 0
	v_mfma_f32_16x16x32_bf16 v[252:255], v[104:107], v[112:115], v[252:255]
	s_waitcnt lgkmcnt(0)
	s_nop 0
	v_mfma_f32_16x16x32_bf16 v[252:255], v[108:111], v[136:139], v[252:255]
	s_branch .Ls2_done3

.Ls2_intra:
	s_ashr_i32 s7, s24, 8
	s_lshl_b32 s7, s7, 11
	s_and_b32 s10, s24, 31
	s_lshl_b32 s10, s10, 6
	s_add_u32 s7, s7, s10
	s_lshl_b32 s7, s7, 12
	s_lshl_b32 s10, s68, 7
	s_add_u32 s7, s7, s10
	s_add_u32 s8, s50, s7
	s_addc_u32 s9, s51, 0
	v_lshlrev_b32_e32 v116, 12, v116
	v_lshl_add_u32 v116, v128, 1, v116
	s_add_u32 s10, s8, 0x0
	s_addc_u32 s11, s9, 0
	v_sub_f32_e32 v96, v146, v237
	v_sub_f32_e32 v97, v146, v238
	v_sub_f32_e32 v98, v146, v239
	v_sub_f32_e32 v99, v146, v123
	v_mul_f32_e32 v96, 0x3fb8aa3b, v96
	v_mul_f32_e32 v97, 0x3fb8aa3b, v97
	v_mul_f32_e32 v98, 0x3fb8aa3b, v98
	v_mul_f32_e32 v99, 0x3fb8aa3b, v99
	v_exp_f32_e32 v96, v96
	v_exp_f32_e32 v97, v97
	v_exp_f32_e32 v98, v98
	v_exp_f32_e32 v99, v99
	v_cmp_ge_i32_e64 vcc, v134, 0
	v_cmp_ge_i32_e64 s[4:5], v134, 16
	v_cmp_ge_i32_e64 s[6:7], v134, 32
	v_mul_f32_e32 v96, v240, v96
	v_mul_f32_e32 v97, v244, v97
	v_mul_f32_e32 v98, v248, v98
	v_mul_f32_e32 v99, v252, v99
	v_cndmask_b32_e64 v96, 0, v96, vcc
	v_cndmask_b32_e64 v97, 0, v97, s[4:5]
	v_cndmask_b32_e64 v98, 0, v98, s[6:7]
	v_cmp_ge_i32_e64 vcc, v134, 48
	v_cvt_pk_bf16_f32 v96, v96, 0
	v_cvt_pk_bf16_f32 v97, v97, 0
	v_cvt_pk_bf16_f32 v98, v98, 0
	v_cndmask_b32_e64 v99, 0, v99, vcc
	v_cvt_pk_bf16_f32 v99, v99, 0
	global_store_short v116, v96, s[10:11] offset:0
	global_store_short v116, v97, s[10:11] offset:32
	global_store_short v116, v98, s[10:11] offset:64
	global_store_short v116, v99, s[10:11] offset:96
	s_add_u32 s10, s8, 0x1000
	s_addc_u32 s11, s9, 0
	v_sub_f32_e32 v100, v147, v237
	v_sub_f32_e32 v101, v147, v238
	v_sub_f32_e32 v102, v147, v239
	v_sub_f32_e64 v103, v147, v123
	v_mul_f32_e32 v100, 0x3fb8aa3b, v100
	v_mul_f32_e32 v101, 0x3fb8aa3b, v101
	v_mul_f32_e32 v102, 0x3fb8aa3b, v102
	v_mul_f32_e32 v103, 0x3fb8aa3b, v103
	v_exp_f32_e32 v100, v100
	v_exp_f32_e32 v101, v101
	v_exp_f32_e32 v102, v102
	v_exp_f32_e32 v103, v103
	v_cmp_ge_i32_e64 vcc, v134, -1
	v_cmp_ge_i32_e64 s[4:5], v134, 15
	v_cmp_ge_i32_e64 s[6:7], v134, 31
	v_mul_f32_e32 v100, v241, v100
	v_mul_f32_e32 v101, v245, v101
	v_mul_f32_e32 v102, v249, v102
	v_mul_f32_e32 v103, v253, v103
	v_cndmask_b32_e64 v100, 0, v100, vcc
	v_cndmask_b32_e64 v101, 0, v101, s[4:5]
	v_cndmask_b32_e64 v102, 0, v102, s[6:7]
	v_cmp_ge_i32_e64 vcc, v134, 47
	v_cvt_pk_bf16_f32 v100, v100, 0
	v_cvt_pk_bf16_f32 v101, v101, 0
	v_cvt_pk_bf16_f32 v102, v102, 0
	v_cndmask_b32_e64 v103, 0, v103, vcc
	v_cvt_pk_bf16_f32 v103, v103, 0
	global_store_short v116, v100, s[10:11] offset:0
	global_store_short v116, v101, s[10:11] offset:32
	global_store_short v116, v102, s[10:11] offset:64
	global_store_short v116, v103, s[10:11] offset:96
	s_add_u32 s10, s8, 0x2000
	s_addc_u32 s11, s9, 0
	v_sub_f32_e32 v104, v148, v237
	v_sub_f32_e32 v105, v148, v238
	v_sub_f32_e32 v106, v148, v239
	v_sub_f32_e64 v107, v148, v123
	v_mul_f32_e32 v104, 0x3fb8aa3b, v104
	v_mul_f32_e32 v105, 0x3fb8aa3b, v105
	v_mul_f32_e32 v106, 0x3fb8aa3b, v106
	v_mul_f32_e32 v107, 0x3fb8aa3b, v107
	v_exp_f32_e32 v104, v104
	v_exp_f32_e32 v105, v105
	v_exp_f32_e32 v106, v106
	v_exp_f32_e32 v107, v107
	v_cmp_ge_i32_e64 vcc, v134, -2
	v_cmp_ge_i32_e64 s[4:5], v134, 14
	v_cmp_ge_i32_e64 s[6:7], v134, 30
	v_mul_f32_e32 v104, v242, v104
	v_mul_f32_e32 v105, v246, v105
	v_mul_f32_e32 v106, v250, v106
	v_mul_f32_e32 v107, v254, v107
	v_cndmask_b32_e64 v104, 0, v104, vcc
	v_cndmask_b32_e64 v105, 0, v105, s[4:5]
	v_cndmask_b32_e64 v106, 0, v106, s[6:7]
	v_cmp_ge_i32_e64 vcc, v134, 46
	v_cvt_pk_bf16_f32 v104, v104, 0
	v_cvt_pk_bf16_f32 v105, v105, 0
	v_cvt_pk_bf16_f32 v106, v106, 0
	v_cndmask_b32_e64 v107, 0, v107, vcc
	v_cvt_pk_bf16_f32 v107, v107, 0
	global_store_short v116, v104, s[10:11] offset:0
	global_store_short v116, v105, s[10:11] offset:32
	global_store_short v116, v106, s[10:11] offset:64
	global_store_short v116, v107, s[10:11] offset:96
	s_add_u32 s10, s8, 0x3000
	s_addc_u32 s11, s9, 0
	v_sub_f32_e32 v108, v149, v237
	v_sub_f32_e32 v109, v149, v238
	v_sub_f32_e32 v110, v149, v239
	v_sub_f32_e64 v111, v149, v123
	v_mul_f32_e32 v108, 0x3fb8aa3b, v108
	v_mul_f32_e32 v109, 0x3fb8aa3b, v109
	v_mul_f32_e32 v110, 0x3fb8aa3b, v110
	v_mul_f32_e32 v111, 0x3fb8aa3b, v111
	v_exp_f32_e32 v108, v108
	v_exp_f32_e32 v109, v109
	v_exp_f32_e32 v110, v110
	v_exp_f32_e32 v111, v111
	v_cmp_ge_i32_e64 vcc, v134, -3
	v_cmp_ge_i32_e64 s[4:5], v134, 13
	v_cmp_ge_i32_e64 s[6:7], v134, 29
	v_mul_f32_e32 v108, v243, v108
	v_mul_f32_e32 v109, v247, v109
	v_mul_f32_e32 v110, v251, v110
	v_mul_f32_e32 v111, v255, v111
	v_cndmask_b32_e64 v108, 0, v108, vcc
	v_cndmask_b32_e64 v109, 0, v109, s[4:5]
	v_cndmask_b32_e64 v110, 0, v110, s[6:7]
	v_cmp_ge_i32_e64 vcc, v134, 45
	v_cvt_pk_bf16_f32 v108, v108, 0
	v_cvt_pk_bf16_f32 v109, v109, 0
	v_cvt_pk_bf16_f32 v110, v110, 0
	v_cndmask_b32_e64 v111, 0, v111, vcc
	v_cvt_pk_bf16_f32 v111, v111, 0
	global_store_short v116, v108, s[10:11] offset:0
	global_store_short v116, v109, s[10:11] offset:32
	global_store_short v116, v110, s[10:11] offset:64
	global_store_short v116, v111, s[10:11] offset:96
.Ls2_end:
	s_waitcnt lgkmcnt(0)
	s_barrier
	s_and_saveexec_b64 s[4:5], s[2:3]
	s_cbranch_execz .LBB0_510
	s_waitcnt lgkmcnt(0)
	v_lshrrev_b32_e32 v252, 4, v198
	s_movk_i32 s8, 0x1080
	v_mul_u32_u24_e32 v252, s8, v252
	v_and_b32_e64 v254, 15, v198
	v_lshl_add_u32 v253, v254, 2, v252
	v_add_u32_e32 v253, 0x15100, v253
	v_add_u32_e32 v252, 0x11000, v252
	ds_read_b32 v237, v252 offset:260
	ds_read_b32 v238, v252 offset:520
	ds_read_b32 v239, v252 offset:780
	ds_read_b32 v240, v252 offset:1040
	ds_read_b32 v241, v252 offset:1300
	ds_read_b32 v242, v252 offset:1560
	ds_read_b32 v243, v252 offset:1820
	ds_read_b32 v244, v252 offset:2080
	ds_read_b32 v245, v252 offset:2340
	ds_read_b32 v246, v252 offset:2600
	ds_read_b32 v247, v252 offset:2860
	ds_read_b32 v248, v252 offset:3120
	ds_read_b32 v249, v252 offset:3380
	ds_read_b32 v250, v252 offset:3640
	ds_read_b32 v251, v252 offset:3900
	v_cmp_eq_u32_e32 vcc, 0, v254
	s_nop 1
	v_cndmask_b32_e64 v96, 0, 1.0, vcc
	v_cmp_eq_u32_e32 vcc, 1, v254
	s_nop 1
	v_cndmask_b32_e64 v97, 0, 1.0, vcc
	v_cmp_eq_u32_e32 vcc, 2, v254
	s_nop 1
	v_cndmask_b32_e64 v98, 0, 1.0, vcc
	v_cmp_eq_u32_e32 vcc, 3, v254
	s_nop 1
	v_cndmask_b32_e64 v99, 0, 1.0, vcc
	v_cmp_eq_u32_e32 vcc, 4, v254
	s_nop 1
	v_cndmask_b32_e64 v100, 0, 1.0, vcc
	v_cmp_eq_u32_e32 vcc, 5, v254
	s_nop 1
	v_cndmask_b32_e64 v101, 0, 1.0, vcc
	v_cmp_eq_u32_e32 vcc, 6, v254
	s_nop 1
	v_cndmask_b32_e64 v102, 0, 1.0, vcc
	v_cmp_eq_u32_e32 vcc, 7, v254
	s_nop 1
	v_cndmask_b32_e64 v103, 0, 1.0, vcc
	v_cmp_eq_u32_e32 vcc, 8, v254
	s_nop 1
	v_cndmask_b32_e64 v104, 0, 1.0, vcc
	v_cmp_eq_u32_e32 vcc, 9, v254
	s_nop 1
	v_cndmask_b32_e64 v105, 0, 1.0, vcc
	v_cmp_eq_u32_e32 vcc, 10, v254
	s_nop 1
	v_cndmask_b32_e64 v106, 0, 1.0, vcc
	v_cmp_eq_u32_e32 vcc, 11, v254
	s_nop 1
	v_cndmask_b32_e64 v107, 0, 1.0, vcc
	v_cmp_eq_u32_e32 vcc, 12, v254
	s_nop 1
	v_cndmask_b32_e64 v108, 0, 1.0, vcc
	v_cmp_eq_u32_e32 vcc, 13, v254
	s_nop 1
	v_cndmask_b32_e64 v109, 0, 1.0, vcc
	v_cmp_eq_u32_e32 vcc, 14, v254
	s_nop 1
	v_cndmask_b32_e64 v110, 0, 1.0, vcc
	v_cmp_eq_u32_e32 vcc, 15, v254
	s_nop 1
	v_cndmask_b32_e64 v111, 0, 1.0, vcc
	s_waitcnt lgkmcnt(0)
	s_nop 0
	ds_read_b32 v112, v252 offset:524
	ds_read_b32 v113, v252 offset:784
	ds_read_b32 v114, v252 offset:1044
	ds_read_b32 v115, v252 offset:1304
	ds_read_b32 v116, v252 offset:1564
	ds_read_b32 v117, v252 offset:1824
	ds_read_b32 v123, v252 offset:2084
	ds_read_b32 v124, v252 offset:2344
	ds_read_b32 v125, v252 offset:2604
	ds_read_b32 v126, v252 offset:2864
	ds_read_b32 v127, v252 offset:3124
	ds_read_b32 v128, v252 offset:3384
	ds_read_b32 v133, v252 offset:3644
	ds_read_b32 v134, v252 offset:3904
	v_fma_f32 v97, -v96, v237, v97
	v_fma_f32 v98, -v96, v238, v98
	v_fma_f32 v99, -v96, v239, v99
	v_fma_f32 v100, -v96, v240, v100
	v_fma_f32 v101, -v96, v241, v101
	v_fma_f32 v102, -v96, v242, v102
	v_fma_f32 v103, -v96, v243, v103
	v_fma_f32 v104, -v96, v244, v104
	v_fma_f32 v105, -v96, v245, v105
	v_fma_f32 v106, -v96, v246, v106
	v_fma_f32 v107, -v96, v247, v107
	v_fma_f32 v108, -v96, v248, v108
	v_fma_f32 v109, -v96, v249, v109
	v_fma_f32 v110, -v96, v250, v110
	v_fma_f32 v111, -v96, v251, v111
	s_waitcnt lgkmcnt(0)
	s_nop 0
	ds_read_b32 v237, v252 offset:788
	ds_read_b32 v238, v252 offset:1048
	ds_read_b32 v239, v252 offset:1308
	ds_read_b32 v240, v252 offset:1568
	ds_read_b32 v241, v252 offset:1828
	ds_read_b32 v242, v252 offset:2088
	ds_read_b32 v243, v252 offset:2348
	ds_read_b32 v244, v252 offset:2608
	ds_read_b32 v245, v252 offset:2868
	ds_read_b32 v246, v252 offset:3128
	ds_read_b32 v247, v252 offset:3388
	ds_read_b32 v248, v252 offset:3648
	ds_read_b32 v249, v252 offset:3908
	v_fma_f32 v98, -v97, v112, v98
	v_fma_f32 v99, -v97, v113, v99
	v_fma_f32 v100, -v97, v114, v100
	v_fma_f32 v101, -v97, v115, v101
	v_fma_f32 v102, -v97, v116, v102
	v_fma_f32 v103, -v97, v117, v103
	v_fma_f32 v104, -v97, v123, v104
	v_fma_f32 v105, -v97, v124, v105
	v_fma_f32 v106, -v97, v125, v106
	v_fma_f32 v107, -v97, v126, v107
	v_fma_f32 v108, -v97, v127, v108
	v_fma_f32 v109, -v97, v128, v109
	v_fma_f32 v110, -v97, v133, v110
	v_fma_f32 v111, -v97, v134, v111
	s_waitcnt lgkmcnt(0)
	s_nop 0
	ds_read_b32 v112, v252 offset:1052
	ds_read_b32 v113, v252 offset:1312
	ds_read_b32 v114, v252 offset:1572
	ds_read_b32 v115, v252 offset:1832
	ds_read_b32 v116, v252 offset:2092
	ds_read_b32 v117, v252 offset:2352
	ds_read_b32 v123, v252 offset:2612
	ds_read_b32 v124, v252 offset:2872
	ds_read_b32 v125, v252 offset:3132
	ds_read_b32 v126, v252 offset:3392
	ds_read_b32 v127, v252 offset:3652
	ds_read_b32 v128, v252 offset:3912
	v_fma_f32 v99, -v98, v237, v99
	v_fma_f32 v100, -v98, v238, v100
	v_fma_f32 v101, -v98, v239, v101
	v_fma_f32 v102, -v98, v240, v102
	v_fma_f32 v103, -v98, v241, v103
	v_fma_f32 v104, -v98, v242, v104
	v_fma_f32 v105, -v98, v243, v105
	v_fma_f32 v106, -v98, v244, v106
	v_fma_f32 v107, -v98, v245, v107
	v_fma_f32 v108, -v98, v246, v108
	v_fma_f32 v109, -v98, v247, v109
	v_fma_f32 v110, -v98, v248, v110
	v_fma_f32 v111, -v98, v249, v111
	s_waitcnt lgkmcnt(0)
	s_nop 0
	ds_read_b32 v237, v252 offset:1316
	ds_read_b32 v238, v252 offset:1576
	ds_read_b32 v239, v252 offset:1836
	ds_read_b32 v240, v252 offset:2096
	ds_read_b32 v241, v252 offset:2356
	ds_read_b32 v242, v252 offset:2616
	ds_read_b32 v243, v252 offset:2876
	ds_read_b32 v244, v252 offset:3136
	ds_read_b32 v245, v252 offset:3396
	ds_read_b32 v246, v252 offset:3656
	ds_read_b32 v247, v252 offset:3916
	v_fma_f32 v100, -v99, v112, v100
	v_fma_f32 v101, -v99, v113, v101
	v_fma_f32 v102, -v99, v114, v102
	v_fma_f32 v103, -v99, v115, v103
	v_fma_f32 v104, -v99, v116, v104
	v_fma_f32 v105, -v99, v117, v105
	v_fma_f32 v106, -v99, v123, v106
	v_fma_f32 v107, -v99, v124, v107
	v_fma_f32 v108, -v99, v125, v108
	v_fma_f32 v109, -v99, v126, v109
	v_fma_f32 v110, -v99, v127, v110
	v_fma_f32 v111, -v99, v128, v111
	s_waitcnt lgkmcnt(0)
	s_nop 0
	ds_read_b32 v112, v252 offset:1580
	ds_read_b32 v113, v252 offset:1840
	ds_read_b32 v114, v252 offset:2100
	ds_read_b32 v115, v252 offset:2360
	ds_read_b32 v116, v252 offset:2620
	ds_read_b32 v117, v252 offset:2880
	ds_read_b32 v123, v252 offset:3140
	ds_read_b32 v124, v252 offset:3400
	ds_read_b32 v125, v252 offset:3660
	ds_read_b32 v126, v252 offset:3920
	v_fma_f32 v101, -v100, v237, v101
	v_fma_f32 v102, -v100, v238, v102
	v_fma_f32 v103, -v100, v239, v103
	v_fma_f32 v104, -v100, v240, v104
	v_fma_f32 v105, -v100, v241, v105
	v_fma_f32 v106, -v100, v242, v106
	v_fma_f32 v107, -v100, v243, v107
	v_fma_f32 v108, -v100, v244, v108
	v_fma_f32 v109, -v100, v245, v109
	v_fma_f32 v110, -v100, v246, v110
	v_fma_f32 v111, -v100, v247, v111
	s_waitcnt lgkmcnt(0)
	s_nop 0
	ds_read_b32 v237, v252 offset:1844
	ds_read_b32 v238, v252 offset:2104
	ds_read_b32 v239, v252 offset:2364
	ds_read_b32 v240, v252 offset:2624
	ds_read_b32 v241, v252 offset:2884
	ds_read_b32 v242, v252 offset:3144
	ds_read_b32 v243, v252 offset:3404
	ds_read_b32 v244, v252 offset:3664
	ds_read_b32 v245, v252 offset:3924
	v_fma_f32 v102, -v101, v112, v102
	v_fma_f32 v103, -v101, v113, v103
	v_fma_f32 v104, -v101, v114, v104
	v_fma_f32 v105, -v101, v115, v105
	v_fma_f32 v106, -v101, v116, v106
	v_fma_f32 v107, -v101, v117, v107
	v_fma_f32 v108, -v101, v123, v108
	v_fma_f32 v109, -v101, v124, v109
	v_fma_f32 v110, -v101, v125, v110
	v_fma_f32 v111, -v101, v126, v111
	s_waitcnt lgkmcnt(0)
	s_nop 0
	ds_read_b32 v112, v252 offset:2108
	ds_read_b32 v113, v252 offset:2368
	ds_read_b32 v114, v252 offset:2628
	ds_read_b32 v115, v252 offset:2888
	ds_read_b32 v116, v252 offset:3148
	ds_read_b32 v117, v252 offset:3408
	ds_read_b32 v123, v252 offset:3668
	ds_read_b32 v124, v252 offset:3928
	v_fma_f32 v103, -v102, v237, v103
	v_fma_f32 v104, -v102, v238, v104
	v_fma_f32 v105, -v102, v239, v105
	v_fma_f32 v106, -v102, v240, v106
	v_fma_f32 v107, -v102, v241, v107
	v_fma_f32 v108, -v102, v242, v108
	v_fma_f32 v109, -v102, v243, v109
	v_fma_f32 v110, -v102, v244, v110
	v_fma_f32 v111, -v102, v245, v111
	s_waitcnt lgkmcnt(0)
	s_nop 0
	ds_read_b32 v237, v252 offset:2372
	ds_read_b32 v238, v252 offset:2632
	ds_read_b32 v239, v252 offset:2892
	ds_read_b32 v240, v252 offset:3152
	ds_read_b32 v241, v252 offset:3412
	ds_read_b32 v242, v252 offset:3672
	ds_read_b32 v243, v252 offset:3932
	v_fma_f32 v104, -v103, v112, v104
	v_fma_f32 v105, -v103, v113, v105
	v_fma_f32 v106, -v103, v114, v106
	v_fma_f32 v107, -v103, v115, v107
	v_fma_f32 v108, -v103, v116, v108
	v_fma_f32 v109, -v103, v117, v109
	v_fma_f32 v110, -v103, v123, v110
	v_fma_f32 v111, -v103, v124, v111
	s_waitcnt lgkmcnt(0)
	s_nop 0
	ds_read_b32 v112, v252 offset:2636
	ds_read_b32 v113, v252 offset:2896
	ds_read_b32 v114, v252 offset:3156
	ds_read_b32 v115, v252 offset:3416
	ds_read_b32 v116, v252 offset:3676
	ds_read_b32 v117, v252 offset:3936
	v_fma_f32 v105, -v104, v237, v105
	v_fma_f32 v106, -v104, v238, v106
	v_fma_f32 v107, -v104, v239, v107
	v_fma_f32 v108, -v104, v240, v108
	v_fma_f32 v109, -v104, v241, v109
	v_fma_f32 v110, -v104, v242, v110
	v_fma_f32 v111, -v104, v243, v111
	s_waitcnt lgkmcnt(0)
	s_nop 0
	ds_read_b32 v237, v252 offset:2900
	ds_read_b32 v238, v252 offset:3160
	ds_read_b32 v239, v252 offset:3420
	ds_read_b32 v240, v252 offset:3680
	ds_read_b32 v241, v252 offset:3940
	v_fma_f32 v106, -v105, v112, v106
	v_fma_f32 v107, -v105, v113, v107
	v_fma_f32 v108, -v105, v114, v108
	v_fma_f32 v109, -v105, v115, v109
	v_fma_f32 v110, -v105, v116, v110
	v_fma_f32 v111, -v105, v117, v111
	s_waitcnt lgkmcnt(0)
	s_nop 0
	ds_read_b32 v112, v252 offset:3164
	ds_read_b32 v113, v252 offset:3424
	ds_read_b32 v114, v252 offset:3684
	ds_read_b32 v115, v252 offset:3944
	v_fma_f32 v107, -v106, v237, v107
	v_fma_f32 v108, -v106, v238, v108
	v_fma_f32 v109, -v106, v239, v109
	v_fma_f32 v110, -v106, v240, v110
	v_fma_f32 v111, -v106, v241, v111
	s_waitcnt lgkmcnt(0)
	s_nop 0
	ds_read_b32 v237, v252 offset:3428
	ds_read_b32 v238, v252 offset:3688
	ds_read_b32 v239, v252 offset:3948
	v_fma_f32 v108, -v107, v112, v108
	v_fma_f32 v109, -v107, v113, v109
	v_fma_f32 v110, -v107, v114, v110
	v_fma_f32 v111, -v107, v115, v111
	s_waitcnt lgkmcnt(0)
	s_nop 0
	ds_read_b32 v112, v252 offset:3692
	ds_read_b32 v113, v252 offset:3952
	v_fma_f32 v109, -v108, v237, v109
	v_fma_f32 v110, -v108, v238, v110
	v_fma_f32 v111, -v108, v239, v111
	s_waitcnt lgkmcnt(0)
	s_nop 0
	ds_read_b32 v237, v252 offset:3956
	v_fma_f32 v110, -v109, v112, v110
	v_fma_f32 v111, -v109, v113, v111
	s_waitcnt lgkmcnt(0)
	s_nop 0
	v_fma_f32 v111, -v110, v237, v111
	ds_write_b32 v253, v96 offset:0
	ds_write_b32 v253, v97 offset:260
	ds_write_b32 v253, v98 offset:520
	ds_write_b32 v253, v99 offset:780
	ds_write_b32 v253, v100 offset:1040
	ds_write_b32 v253, v101 offset:1300
	ds_write_b32 v253, v102 offset:1560
	ds_write_b32 v253, v103 offset:1820
	ds_write_b32 v253, v104 offset:2080
	ds_write_b32 v253, v105 offset:2340
	ds_write_b32 v253, v106 offset:2600
	ds_write_b32 v253, v107 offset:2860
	ds_write_b32 v253, v108 offset:3120
	ds_write_b32 v253, v109 offset:3380
	ds_write_b32 v253, v110 offset:3640
	ds_write_b32 v253, v111 offset:3900
